# v35 + MLP1 (both layers): wave halves stay staggered through the epilogue (per-unit align/re-stagger barriers dropped)
# baseline (speedup 1.0000x reference)
.LBB0_745:
	ds_read_b128 v[154:157], v150
	ds_read_b128 v[158:161], v150 offset:1024
	ds_read_b128 v[162:165], v150 offset:2048
	ds_read_b128 v[166:169], v150 offset:3072
	ds_read_b128 v[170:173], v151
	ds_read_b128 v[174:177], v151 offset:1024
	ds_read_b128 v[178:181], v151 offset:2048
	ds_read_b128 v[182:185], v151 offset:3072
	s_add_u32 s44, s42, 0xfffc0080
	s_addc_u32 s45, s43, -1
	s_cmp_eq_u32 s68, 12
	s_cselect_b32 s47, s14, s45
	s_cselect_b32 s46, s15, s44
	s_cselect_b32 s45, s21, s67
	s_cselect_b32 s44, s65, s66
	v_lshl_add_u64 v[146:147], s[42:43], 0, v[138:139]
	s_add_i32 m0, s19, 0xc000
	ds_read_b128 v[186:189], v152
	ds_read_b128 v[190:193], v152 offset:1024
	ds_read_b128 v[194:197], v152 offset:2048
	ds_read_b128 v[198:201], v152 offset:3072
	ds_read_b128 v[206:209], v152 offset:4096
	ds_read_b128 v[210:213], v152 offset:5120
	ds_read_b128 v[214:217], v152 offset:6144
	ds_read_b128 v[218:221], v152 offset:7168
	global_load_lds_dwordx4 v[146:147], off
	v_lshl_add_u64 v[146:147], s[42:43], 0, v[140:141]
	s_add_i32 m0, s19, 0xe000
	s_nop 0
	global_load_lds_dwordx4 v[146:147], off
	s_waitcnt vmcnt(8)
	s_waitcnt lgkmcnt(0)
	s_barrier
	s_setprio 1
	s_waitcnt lgkmcnt(0)
	v_mfma_f32_16x16x32_bf16 v[126:129], v[154:157], v[186:189], v[126:129]
	v_mfma_f32_16x16x32_bf16 v[122:125], v[162:165], v[186:189], v[122:125]
	v_mfma_f32_16x16x32_bf16 v[110:113], v[154:157], v[194:197], v[110:113]
	v_mfma_f32_16x16x32_bf16 v[106:109], v[162:165], v[194:197], v[106:109]
	v_mfma_f32_16x16x32_bf16 v[94:97], v[154:157], v[206:209], v[94:97]
	v_mfma_f32_16x16x32_bf16 v[90:93], v[162:165], v[206:209], v[90:93]
	v_mfma_f32_16x16x32_bf16 v[78:81], v[154:157], v[214:217], v[78:81]
	v_mfma_f32_16x16x32_bf16 v[74:77], v[162:165], v[214:217], v[74:77]
	v_mfma_f32_16x16x32_bf16 v[126:129], v[158:161], v[190:193], v[126:129]
	v_mfma_f32_16x16x32_bf16 v[122:125], v[166:169], v[190:193], v[122:125]
	v_mfma_f32_16x16x32_bf16 v[110:113], v[158:161], v[198:201], v[110:113]
	v_mfma_f32_16x16x32_bf16 v[106:109], v[166:169], v[198:201], v[106:109]
	v_mfma_f32_16x16x32_bf16 v[94:97], v[158:161], v[210:213], v[94:97]
	v_mfma_f32_16x16x32_bf16 v[90:93], v[166:169], v[210:213], v[90:93]
	v_mfma_f32_16x16x32_bf16 v[78:81], v[158:161], v[218:221], v[78:81]
	v_mfma_f32_16x16x32_bf16 v[74:77], v[166:169], v[218:221], v[74:77]
	s_setprio 0
	s_setprio 1
	v_mfma_f32_16x16x32_bf16 v[118:121], v[170:173], v[186:189], v[118:121]
	v_mfma_f32_16x16x32_bf16 v[114:117], v[178:181], v[186:189], v[114:117]
	v_mfma_f32_16x16x32_bf16 v[102:105], v[170:173], v[194:197], v[102:105]
	v_mfma_f32_16x16x32_bf16 v[98:101], v[178:181], v[194:197], v[98:101]
	v_mfma_f32_16x16x32_bf16 v[86:89], v[170:173], v[206:209], v[86:89]
	v_mfma_f32_16x16x32_bf16 v[82:85], v[178:181], v[206:209], v[82:85]
	v_mfma_f32_16x16x32_bf16 v[70:73], v[170:173], v[214:217], v[70:73]
	v_mfma_f32_16x16x32_bf16 v[66:69], v[178:181], v[214:217], v[66:69]
	v_mfma_f32_16x16x32_bf16 v[118:121], v[174:177], v[190:193], v[118:121]
	v_mfma_f32_16x16x32_bf16 v[114:117], v[182:185], v[190:193], v[114:117]
	v_mfma_f32_16x16x32_bf16 v[102:105], v[174:177], v[198:201], v[102:105]
	v_mfma_f32_16x16x32_bf16 v[98:101], v[182:185], v[198:201], v[98:101]
	v_mfma_f32_16x16x32_bf16 v[86:89], v[174:177], v[210:213], v[86:89]
	v_mfma_f32_16x16x32_bf16 v[82:85], v[182:185], v[210:213], v[82:85]
	v_mfma_f32_16x16x32_bf16 v[70:73], v[174:177], v[218:221], v[70:73]
	v_mfma_f32_16x16x32_bf16 v[66:69], v[182:185], v[218:221], v[66:69]
	s_setprio 0
	s_barrier
	s_add_i32 s69, s49, s16
	v_lshl_add_u64 v[146:147], s[44:45], 0, v[134:135]
	s_mov_b32 m0, s69
	ds_read_b128 v[186:189], v152 offset:16384
	ds_read_b128 v[190:193], v152 offset:17408
	ds_read_b128 v[194:197], v152 offset:18432
	ds_read_b128 v[198:201], v152 offset:19456
	ds_read_b128 v[206:209], v152 offset:20480
	ds_read_b128 v[210:213], v152 offset:21504
	ds_read_b128 v[214:217], v152 offset:22528
	ds_read_b128 v[218:221], v152 offset:23552
	global_load_lds_dwordx4 v[146:147], off
	s_add_i32 m0, s69, 0x2000
	s_add_u32 s70, s44, 0x40000
	v_lshl_add_u64 v[202:203], s[44:45], 0, v[130:131]
	s_addc_u32 s71, s45, 0
	s_add_i32 s69, s62, s16
	global_load_lds_dwordx4 v[202:203], off
	v_lshl_add_u64 v[222:223], s[70:71], 0, v[134:135]
	s_mov_b32 m0, s69
	v_lshl_add_u64 v[224:225], s[46:47], 0, v[132:133]
	global_load_lds_dwordx4 v[222:223], off
	v_lshl_add_u64 v[222:223], s[70:71], 0, v[130:131]
	s_add_i32 m0, s69, 0x2000
	s_nop 0
	global_load_lds_dwordx4 v[222:223], off
	v_lshl_add_u64 v[222:223], s[46:47], 0, v[136:137]
	s_mov_b32 m0, s19
	s_nop 0
	global_load_lds_dwordx4 v[222:223], off
	s_mov_b32 m0, s24
	s_nop 0
	global_load_lds_dwordx4 v[224:225], off
	s_waitcnt vmcnt(8)
	s_waitcnt lgkmcnt(0)
	s_barrier
	s_setprio 1
	s_waitcnt lgkmcnt(0)
	v_mfma_f32_16x16x32_bf16 v[62:65], v[154:157], v[186:189], v[62:65]
	v_mfma_f32_16x16x32_bf16 v[58:61], v[162:165], v[186:189], v[58:61]
	v_mfma_f32_16x16x32_bf16 v[46:49], v[154:157], v[194:197], v[46:49]
	v_mfma_f32_16x16x32_bf16 v[42:45], v[162:165], v[194:197], v[42:45]
	v_mfma_f32_16x16x32_bf16 v[30:33], v[154:157], v[206:209], v[30:33]
	v_mfma_f32_16x16x32_bf16 v[26:29], v[162:165], v[206:209], v[26:29]
	v_mfma_f32_16x16x32_bf16 v[14:17], v[154:157], v[214:217], v[14:17]
	v_mfma_f32_16x16x32_bf16 v[10:13], v[162:165], v[214:217], v[10:13]
	v_mfma_f32_16x16x32_bf16 v[62:65], v[158:161], v[190:193], v[62:65]
	v_mfma_f32_16x16x32_bf16 v[58:61], v[166:169], v[190:193], v[58:61]
	v_mfma_f32_16x16x32_bf16 v[46:49], v[158:161], v[198:201], v[46:49]
	v_mfma_f32_16x16x32_bf16 v[42:45], v[166:169], v[198:201], v[42:45]
	v_mfma_f32_16x16x32_bf16 v[30:33], v[158:161], v[210:213], v[30:33]
	v_mfma_f32_16x16x32_bf16 v[26:29], v[166:169], v[210:213], v[26:29]
	v_mfma_f32_16x16x32_bf16 v[14:17], v[158:161], v[218:221], v[14:17]
	v_mfma_f32_16x16x32_bf16 v[10:13], v[166:169], v[218:221], v[10:13]
	s_setprio 0
	s_setprio 1
	v_mfma_f32_16x16x32_bf16 v[54:57], v[170:173], v[186:189], v[54:57]
	v_mfma_f32_16x16x32_bf16 v[50:53], v[178:181], v[186:189], v[50:53]
	v_mfma_f32_16x16x32_bf16 v[38:41], v[170:173], v[194:197], v[38:41]
	v_mfma_f32_16x16x32_bf16 v[34:37], v[178:181], v[194:197], v[34:37]
	v_mfma_f32_16x16x32_bf16 v[22:25], v[170:173], v[206:209], v[22:25]
	v_mfma_f32_16x16x32_bf16 v[18:21], v[178:181], v[206:209], v[18:21]
	v_mfma_f32_16x16x32_bf16 v[6:9], v[170:173], v[214:217], v[6:9]
	v_mfma_f32_16x16x32_bf16 v[2:5], v[178:181], v[214:217], v[2:5]
	v_mfma_f32_16x16x32_bf16 v[54:57], v[174:177], v[190:193], v[54:57]
	v_mfma_f32_16x16x32_bf16 v[50:53], v[182:185], v[190:193], v[50:53]
	v_mfma_f32_16x16x32_bf16 v[38:41], v[174:177], v[198:201], v[38:41]
	v_mfma_f32_16x16x32_bf16 v[34:37], v[182:185], v[198:201], v[34:37]
	v_mfma_f32_16x16x32_bf16 v[22:25], v[174:177], v[210:213], v[22:25]
	v_mfma_f32_16x16x32_bf16 v[18:21], v[182:185], v[210:213], v[18:21]
	v_mfma_f32_16x16x32_bf16 v[6:9], v[174:177], v[218:221], v[6:9]
	v_mfma_f32_16x16x32_bf16 v[2:5], v[182:185], v[218:221], v[2:5]
	s_setprio 0
	s_barrier
	s_add_i32 s69, 0, 0x18000
	v_add_u32_e32 v153, s69, v149
	s_add_i32 s70, 0, 0x1c000
	ds_read_b128 v[154:157], v153
	ds_read_b128 v[158:161], v153 offset:1024
	ds_read_b128 v[162:165], v153 offset:2048
	ds_read_b128 v[166:169], v153 offset:3072
	v_add_u32_e32 v153, s70, v149
	ds_read_b128 v[170:173], v153
	ds_read_b128 v[174:177], v153 offset:1024
	ds_read_b128 v[178:181], v153 offset:2048
	ds_read_b128 v[182:185], v153 offset:3072
	s_add_u32 s46, s46, 0x40000
	s_addc_u32 s47, s47, 0
	s_mov_b32 m0, s25
	v_lshl_add_u64 v[226:227], s[46:47], 0, v[136:137]
	ds_read_b128 v[186:189], v152 offset:32768
	ds_read_b128 v[190:193], v152 offset:33792
	ds_read_b128 v[194:197], v152 offset:34816
	ds_read_b128 v[198:201], v152 offset:35840
	ds_read_b128 v[206:209], v152 offset:36864
	ds_read_b128 v[210:213], v152 offset:37888
	ds_read_b128 v[214:217], v152 offset:38912
	ds_read_b128 v[218:221], v152 offset:39936
	global_load_lds_dwordx4 v[226:227], off
	v_lshl_add_u64 v[226:227], s[46:47], 0, v[132:133]
	s_mov_b32 m0, s28
	s_nop 0
	global_load_lds_dwordx4 v[226:227], off
	s_waitcnt vmcnt(8)
	s_waitcnt lgkmcnt(0)
	s_barrier
	s_setprio 1
	s_waitcnt lgkmcnt(0)
	v_mfma_f32_16x16x32_bf16 v[126:129], v[154:157], v[186:189], v[126:129]
	v_mfma_f32_16x16x32_bf16 v[122:125], v[162:165], v[186:189], v[122:125]
	v_mfma_f32_16x16x32_bf16 v[110:113], v[154:157], v[194:197], v[110:113]
	v_mfma_f32_16x16x32_bf16 v[106:109], v[162:165], v[194:197], v[106:109]
	v_mfma_f32_16x16x32_bf16 v[94:97], v[154:157], v[206:209], v[94:97]
	v_mfma_f32_16x16x32_bf16 v[90:93], v[162:165], v[206:209], v[90:93]
	v_mfma_f32_16x16x32_bf16 v[78:81], v[154:157], v[214:217], v[78:81]
	v_mfma_f32_16x16x32_bf16 v[74:77], v[162:165], v[214:217], v[74:77]
	v_mfma_f32_16x16x32_bf16 v[126:129], v[158:161], v[190:193], v[126:129]
	v_mfma_f32_16x16x32_bf16 v[122:125], v[166:169], v[190:193], v[122:125]
	v_mfma_f32_16x16x32_bf16 v[110:113], v[158:161], v[198:201], v[110:113]
	v_mfma_f32_16x16x32_bf16 v[106:109], v[166:169], v[198:201], v[106:109]
	v_mfma_f32_16x16x32_bf16 v[94:97], v[158:161], v[210:213], v[94:97]
	v_mfma_f32_16x16x32_bf16 v[90:93], v[166:169], v[210:213], v[90:93]
	v_mfma_f32_16x16x32_bf16 v[78:81], v[158:161], v[218:221], v[78:81]
	v_mfma_f32_16x16x32_bf16 v[74:77], v[166:169], v[218:221], v[74:77]
	s_setprio 0
	s_setprio 1
	v_mfma_f32_16x16x32_bf16 v[118:121], v[170:173], v[186:189], v[118:121]
	v_mfma_f32_16x16x32_bf16 v[114:117], v[178:181], v[186:189], v[114:117]
	v_mfma_f32_16x16x32_bf16 v[102:105], v[170:173], v[194:197], v[102:105]
	v_mfma_f32_16x16x32_bf16 v[98:101], v[178:181], v[194:197], v[98:101]
	v_mfma_f32_16x16x32_bf16 v[86:89], v[170:173], v[206:209], v[86:89]
	v_mfma_f32_16x16x32_bf16 v[82:85], v[178:181], v[206:209], v[82:85]
	v_mfma_f32_16x16x32_bf16 v[70:73], v[170:173], v[214:217], v[70:73]
	v_mfma_f32_16x16x32_bf16 v[66:69], v[178:181], v[214:217], v[66:69]
	v_mfma_f32_16x16x32_bf16 v[118:121], v[174:177], v[190:193], v[118:121]
	v_mfma_f32_16x16x32_bf16 v[114:117], v[182:185], v[190:193], v[114:117]
	v_mfma_f32_16x16x32_bf16 v[102:105], v[174:177], v[198:201], v[102:105]
	v_mfma_f32_16x16x32_bf16 v[98:101], v[182:185], v[198:201], v[98:101]
	v_mfma_f32_16x16x32_bf16 v[86:89], v[174:177], v[210:213], v[86:89]
	v_mfma_f32_16x16x32_bf16 v[82:85], v[182:185], v[210:213], v[82:85]
	v_mfma_f32_16x16x32_bf16 v[70:73], v[174:177], v[218:221], v[70:73]
	v_mfma_f32_16x16x32_bf16 v[66:69], v[182:185], v[218:221], v[66:69]
	s_setprio 0
	s_barrier
	s_add_i32 s46, s69, s16
	v_lshl_add_u64 v[146:147], v[146:147], 0, s[10:11]
	s_mov_b32 m0, s46
	ds_read_b128 v[186:189], v152 offset:49152
	ds_read_b128 v[190:193], v152 offset:50176
	ds_read_b128 v[194:197], v152 offset:51200
	ds_read_b128 v[198:201], v152 offset:52224
	ds_read_b128 v[206:209], v152 offset:53248
	ds_read_b128 v[210:213], v152 offset:54272
	ds_read_b128 v[214:217], v152 offset:55296
	ds_read_b128 v[218:221], v152 offset:56320
	global_load_lds_dwordx4 v[146:147], off
	s_add_i32 m0, s46, 0x2000
	s_add_u32 s44, s44, 0x40080
	v_lshl_add_u64 v[146:147], v[202:203], 0, s[10:11]
	s_addc_u32 s45, s45, 0
	s_add_i32 s46, s70, s16
	global_load_lds_dwordx4 v[146:147], off
	v_lshl_add_u64 v[146:147], s[44:45], 0, v[134:135]
	s_mov_b32 m0, s46
	s_nop 0
	global_load_lds_dwordx4 v[146:147], off
	v_lshl_add_u64 v[146:147], s[44:45], 0, v[130:131]
	s_add_i32 m0, s46, 0x2000
	s_nop 0
	global_load_lds_dwordx4 v[146:147], off
	v_lshl_add_u64 v[146:147], v[222:223], 0, s[10:11]
	s_mov_b32 m0, s33
	s_nop 0
	global_load_lds_dwordx4 v[146:147], off
	v_lshl_add_u64 v[146:147], v[224:225], 0, s[10:11]
	s_mov_b32 m0, s35
	s_nop 0
	global_load_lds_dwordx4 v[146:147], off
	s_waitcnt vmcnt(8)
	s_waitcnt lgkmcnt(0)
	s_barrier
	s_setprio 1
	s_waitcnt lgkmcnt(0)
	v_mfma_f32_16x16x32_bf16 v[62:65], v[154:157], v[186:189], v[62:65]
	v_mfma_f32_16x16x32_bf16 v[58:61], v[162:165], v[186:189], v[58:61]
	v_mfma_f32_16x16x32_bf16 v[46:49], v[154:157], v[194:197], v[46:49]
	v_mfma_f32_16x16x32_bf16 v[42:45], v[162:165], v[194:197], v[42:45]
	v_mfma_f32_16x16x32_bf16 v[30:33], v[154:157], v[206:209], v[30:33]
	v_mfma_f32_16x16x32_bf16 v[26:29], v[162:165], v[206:209], v[26:29]
	v_mfma_f32_16x16x32_bf16 v[14:17], v[154:157], v[214:217], v[14:17]
	v_mfma_f32_16x16x32_bf16 v[10:13], v[162:165], v[214:217], v[10:13]
	v_mfma_f32_16x16x32_bf16 v[62:65], v[158:161], v[190:193], v[62:65]
	v_mfma_f32_16x16x32_bf16 v[58:61], v[166:169], v[190:193], v[58:61]
	v_mfma_f32_16x16x32_bf16 v[46:49], v[158:161], v[198:201], v[46:49]
	v_mfma_f32_16x16x32_bf16 v[42:45], v[166:169], v[198:201], v[42:45]
	v_mfma_f32_16x16x32_bf16 v[30:33], v[158:161], v[210:213], v[30:33]
	v_mfma_f32_16x16x32_bf16 v[26:29], v[166:169], v[210:213], v[26:29]
	v_mfma_f32_16x16x32_bf16 v[14:17], v[158:161], v[218:221], v[14:17]
	v_mfma_f32_16x16x32_bf16 v[10:13], v[166:169], v[218:221], v[10:13]
	s_setprio 0
	s_setprio 1
	v_mfma_f32_16x16x32_bf16 v[54:57], v[170:173], v[186:189], v[54:57]
	v_mfma_f32_16x16x32_bf16 v[50:53], v[178:181], v[186:189], v[50:53]
	v_mfma_f32_16x16x32_bf16 v[38:41], v[170:173], v[194:197], v[38:41]
	v_mfma_f32_16x16x32_bf16 v[34:37], v[178:181], v[194:197], v[34:37]
	v_mfma_f32_16x16x32_bf16 v[22:25], v[170:173], v[206:209], v[22:25]
	v_mfma_f32_16x16x32_bf16 v[18:21], v[178:181], v[206:209], v[18:21]
	v_mfma_f32_16x16x32_bf16 v[6:9], v[170:173], v[214:217], v[6:9]
	v_mfma_f32_16x16x32_bf16 v[2:5], v[178:181], v[214:217], v[2:5]
	v_mfma_f32_16x16x32_bf16 v[54:57], v[174:177], v[190:193], v[54:57]
	v_mfma_f32_16x16x32_bf16 v[50:53], v[182:185], v[190:193], v[50:53]
	v_mfma_f32_16x16x32_bf16 v[38:41], v[174:177], v[198:201], v[38:41]
	v_mfma_f32_16x16x32_bf16 v[34:37], v[182:185], v[198:201], v[34:37]
	v_mfma_f32_16x16x32_bf16 v[22:25], v[174:177], v[210:213], v[22:25]
	v_mfma_f32_16x16x32_bf16 v[18:21], v[182:185], v[210:213], v[18:21]
	v_mfma_f32_16x16x32_bf16 v[6:9], v[174:177], v[218:221], v[6:9]
	v_mfma_f32_16x16x32_bf16 v[2:5], v[182:185], v[218:221], v[2:5]
	s_setprio 0
	s_barrier
	s_add_i32 s68, s68, 2
	s_add_u32 s42, s42, 0x100
	s_addc_u32 s43, s43, 0
	s_add_u32 s66, s66, 0x100
	s_addc_u32 s67, s67, 0
	s_cmp_gt_u32 s68, 13
	s_cbranch_scc0 .LBB0_745
	s_cmp_lg_u64 s[4:5], 0
	s_cbranch_scc1 .LBB0_748
	s_and_b64 vcc, exec, s[12:13]
	s_cbranch_vccz .LBB0_748
	s_barrier
.LBB0_748:
	s_lshl_b32 s14, s34, 8
	s_ashr_i32 s15, s14, 31
	s_lshl_b64 s[14:15], s[14:15], 13
	s_add_u32 s21, s0, s14
	s_addc_u32 s34, s1, s15
	s_lshl_b32 s14, s64, 8
	v_mov_b32_e32 v146, v1
	v_mov_b32_e32 v147, v148
	s_ashr_i32 s15, s14, 31
	s_lshl_b64 s[14:15], s[14:15], 1
	v_add_u32_e32 v146, s30, v146
	v_max_f32_e32 v126, 0, v126
	v_max_f32_e32 v122, 0, v122
	v_max_f32_e32 v127, 0, v127
	v_max_f32_e32 v123, 0, v123
	s_add_u32 s42, s21, s14
	v_lshl_add_u32 v154, v147, 3, s31
	v_ashrrev_i32_e32 v147, 31, v146
	v_pk_mul_f32 v[126:127], v[126:127], v[126:127]
	v_pk_mul_f32 v[122:123], v[122:123], v[122:123]
	v_max_f32_e32 v128, 0, v128
	v_max_f32_e32 v124, 0, v124
	v_max_f32_e32 v129, 0, v129
	v_max_f32_e32 v125, 0, v125
	s_addc_u32 s43, s34, s15
	v_pk_mul_f32 v[128:129], v[128:129], v[128:129]
	v_pk_mul_f32 v[156:157], v[124:125], v[124:125]
	v_cvt_pk_bf16_f32 v124, v126, v127
	v_cvt_pk_bf16_f32 v126, v122, v123
	v_lshlrev_b64 v[122:123], 13, v[146:147]
	v_ashrrev_i32_e32 v155, 31, v154
	v_cvt_pk_bf16_f32 v125, v128, v129
	v_lshl_add_u64 v[128:129], s[42:43], 0, v[122:123]
	v_lshlrev_b64 v[122:123], 1, v[154:155]
	v_cvt_pk_bf16_f32 v127, v156, v157
	v_lshl_add_u64 v[128:129], v[128:129], 0, v[122:123]
	v_max_f32_e32 v114, 0, v114
	v_max_f32_e32 v115, 0, v115
	global_store_dwordx4 v[128:129], v[124:127], off
	s_nop 1
	v_pk_mul_f32 v[124:125], v[114:115], v[114:115]
	v_max_f32_e32 v116, 0, v116
	v_max_f32_e32 v118, 0, v118
	v_max_f32_e32 v119, 0, v119
	v_max_f32_e32 v114, 0, v120
	v_max_f32_e32 v115, 0, v121
	v_max_f32_e32 v117, 0, v117
	v_pk_mul_f32 v[118:119], v[118:119], v[118:119]
	v_pk_mul_f32 v[120:121], v[114:115], v[114:115]
	v_pk_mul_f32 v[126:127], v[116:117], v[116:117]
	v_cvt_pk_bf16_f32 v114, v118, v119
	v_cvt_pk_bf16_f32 v115, v120, v121
	v_cvt_pk_bf16_f32 v116, v124, v125
	v_cvt_pk_bf16_f32 v117, v126, v127
	v_max_f32_e32 v106, 0, v106
	v_max_f32_e32 v107, 0, v107
	global_store_dwordx4 v[128:129], v[114:117], off offset:256
	s_nop 1
	v_pk_mul_f32 v[116:117], v[106:107], v[106:107]
	v_add_u32_e32 v114, 16, v146
	v_max_f32_e32 v110, 0, v110
	v_max_f32_e32 v111, 0, v111
	v_max_f32_e32 v108, 0, v108
	v_ashrrev_i32_e32 v115, 31, v114
	v_pk_mul_f32 v[110:111], v[110:111], v[110:111]
	v_max_f32_e32 v106, 0, v112
	v_max_f32_e32 v107, 0, v113
	v_max_f32_e32 v109, 0, v109
	v_pk_mul_f32 v[112:113], v[106:107], v[106:107]
	v_cvt_pk_bf16_f32 v106, v110, v111
	v_lshlrev_b64 v[110:111], 13, v[114:115]
	v_pk_mul_f32 v[118:119], v[108:109], v[108:109]
	v_lshl_add_u64 v[110:111], s[42:43], 0, v[110:111]
	v_cvt_pk_bf16_f32 v107, v112, v113
	v_cvt_pk_bf16_f32 v108, v116, v117
	v_cvt_pk_bf16_f32 v109, v118, v119
	v_lshl_add_u64 v[110:111], v[110:111], 0, v[122:123]
	v_max_f32_e32 v98, 0, v98
	v_max_f32_e32 v99, 0, v99
	global_store_dwordx4 v[110:111], v[106:109], off
	s_nop 1
	v_pk_mul_f32 v[106:107], v[98:99], v[98:99]
	v_max_f32_e32 v100, 0, v100
	v_max_f32_e32 v102, 0, v102
	v_max_f32_e32 v103, 0, v103
	v_max_f32_e32 v98, 0, v104
	v_max_f32_e32 v99, 0, v105
	v_max_f32_e32 v101, 0, v101
	v_pk_mul_f32 v[102:103], v[102:103], v[102:103]
	v_pk_mul_f32 v[104:105], v[98:99], v[98:99]
	v_pk_mul_f32 v[108:109], v[100:101], v[100:101]
	v_cvt_pk_bf16_f32 v98, v102, v103
	v_cvt_pk_bf16_f32 v99, v104, v105
	v_cvt_pk_bf16_f32 v100, v106, v107
	v_cvt_pk_bf16_f32 v101, v108, v109
	v_max_f32_e32 v90, 0, v90
	v_max_f32_e32 v91, 0, v91
	global_store_dwordx4 v[110:111], v[98:101], off offset:256
	s_nop 1
	v_pk_mul_f32 v[100:101], v[90:91], v[90:91]
	v_add_u32_e32 v98, 32, v146
	v_max_f32_e32 v94, 0, v94
	v_max_f32_e32 v95, 0, v95
	v_max_f32_e32 v92, 0, v92
	v_ashrrev_i32_e32 v99, 31, v98
	v_pk_mul_f32 v[94:95], v[94:95], v[94:95]
	v_max_f32_e32 v90, 0, v96
	v_max_f32_e32 v91, 0, v97
	v_max_f32_e32 v93, 0, v93
	v_pk_mul_f32 v[96:97], v[90:91], v[90:91]
	v_cvt_pk_bf16_f32 v90, v94, v95
	v_lshlrev_b64 v[94:95], 13, v[98:99]
	v_pk_mul_f32 v[102:103], v[92:93], v[92:93]
	v_lshl_add_u64 v[94:95], s[42:43], 0, v[94:95]
	v_cvt_pk_bf16_f32 v91, v96, v97
	v_cvt_pk_bf16_f32 v92, v100, v101
	v_cvt_pk_bf16_f32 v93, v102, v103
	v_lshl_add_u64 v[94:95], v[94:95], 0, v[122:123]
	v_max_f32_e32 v82, 0, v82
	v_max_f32_e32 v83, 0, v83
	global_store_dwordx4 v[94:95], v[90:93], off
	s_nop 1
	v_pk_mul_f32 v[90:91], v[82:83], v[82:83]
	v_max_f32_e32 v84, 0, v84
	v_max_f32_e32 v86, 0, v86
	v_max_f32_e32 v87, 0, v87
	v_max_f32_e32 v82, 0, v88
	v_max_f32_e32 v83, 0, v89
	v_max_f32_e32 v85, 0, v85
	v_pk_mul_f32 v[86:87], v[86:87], v[86:87]
	v_pk_mul_f32 v[88:89], v[82:83], v[82:83]
	v_pk_mul_f32 v[92:93], v[84:85], v[84:85]
	v_cvt_pk_bf16_f32 v82, v86, v87
	v_cvt_pk_bf16_f32 v83, v88, v89
	v_cvt_pk_bf16_f32 v84, v90, v91
	v_cvt_pk_bf16_f32 v85, v92, v93
	v_max_f32_e32 v74, 0, v74
	v_max_f32_e32 v75, 0, v75
	global_store_dwordx4 v[94:95], v[82:85], off offset:256
	s_nop 1
	v_pk_mul_f32 v[84:85], v[74:75], v[74:75]
	v_add_u32_e32 v82, 48, v146
	v_max_f32_e32 v78, 0, v78
	v_max_f32_e32 v79, 0, v79
	v_max_f32_e32 v76, 0, v76
	v_ashrrev_i32_e32 v83, 31, v82
	v_pk_mul_f32 v[78:79], v[78:79], v[78:79]
	v_max_f32_e32 v74, 0, v80
	v_max_f32_e32 v75, 0, v81
	v_max_f32_e32 v77, 0, v77
	v_pk_mul_f32 v[80:81], v[74:75], v[74:75]
	v_cvt_pk_bf16_f32 v74, v78, v79
	v_lshlrev_b64 v[78:79], 13, v[82:83]
	v_pk_mul_f32 v[86:87], v[76:77], v[76:77]
	v_lshl_add_u64 v[78:79], s[42:43], 0, v[78:79]
	v_cvt_pk_bf16_f32 v75, v80, v81
	v_cvt_pk_bf16_f32 v76, v84, v85
	v_cvt_pk_bf16_f32 v77, v86, v87
	v_lshl_add_u64 v[78:79], v[78:79], 0, v[122:123]
	v_max_f32_e32 v66, 0, v66
	v_max_f32_e32 v67, 0, v67
	global_store_dwordx4 v[78:79], v[74:77], off
	s_nop 1
	v_pk_mul_f32 v[74:75], v[66:67], v[66:67]
	v_max_f32_e32 v68, 0, v68
	v_max_f32_e32 v70, 0, v70
	v_max_f32_e32 v71, 0, v71
	v_max_f32_e32 v66, 0, v72
	v_max_f32_e32 v67, 0, v73
	v_max_f32_e32 v69, 0, v69
	v_pk_mul_f32 v[70:71], v[70:71], v[70:71]
	v_pk_mul_f32 v[72:73], v[66:67], v[66:67]
	v_pk_mul_f32 v[76:77], v[68:69], v[68:69]
	v_cvt_pk_bf16_f32 v66, v70, v71
	v_cvt_pk_bf16_f32 v67, v72, v73
	v_cvt_pk_bf16_f32 v68, v74, v75
	v_cvt_pk_bf16_f32 v69, v76, v77
	v_max_f32_e32 v58, 0, v58
	v_max_f32_e32 v59, 0, v59
	global_store_dwordx4 v[78:79], v[66:69], off offset:256
	s_nop 1
	v_pk_mul_f32 v[68:69], v[58:59], v[58:59]
	v_add_u32_e32 v66, 0x80, v146
	v_max_f32_e32 v62, 0, v62
	v_max_f32_e32 v63, 0, v63
	v_max_f32_e32 v60, 0, v60
	v_ashrrev_i32_e32 v67, 31, v66
	v_pk_mul_f32 v[62:63], v[62:63], v[62:63]
	v_max_f32_e32 v58, 0, v64
	v_max_f32_e32 v59, 0, v65
	v_max_f32_e32 v61, 0, v61
	v_pk_mul_f32 v[64:65], v[58:59], v[58:59]
	v_cvt_pk_bf16_f32 v58, v62, v63
	v_lshlrev_b64 v[62:63], 13, v[66:67]
	v_pk_mul_f32 v[70:71], v[60:61], v[60:61]
	v_lshl_add_u64 v[62:63], s[42:43], 0, v[62:63]
	v_cvt_pk_bf16_f32 v59, v64, v65
	v_cvt_pk_bf16_f32 v60, v68, v69
	v_cvt_pk_bf16_f32 v61, v70, v71
	v_lshl_add_u64 v[62:63], v[62:63], 0, v[122:123]
	v_max_f32_e32 v50, 0, v50
	v_max_f32_e32 v51, 0, v51
	global_store_dwordx4 v[62:63], v[58:61], off
	s_nop 1
	v_pk_mul_f32 v[58:59], v[50:51], v[50:51]
	v_max_f32_e32 v52, 0, v52
	v_max_f32_e32 v54, 0, v54
	v_max_f32_e32 v55, 0, v55
	v_max_f32_e32 v50, 0, v56
	v_max_f32_e32 v51, 0, v57
	v_max_f32_e32 v53, 0, v53
	v_pk_mul_f32 v[54:55], v[54:55], v[54:55]
	v_pk_mul_f32 v[56:57], v[50:51], v[50:51]
	v_pk_mul_f32 v[60:61], v[52:53], v[52:53]
	v_cvt_pk_bf16_f32 v50, v54, v55
	v_cvt_pk_bf16_f32 v51, v56, v57
	v_cvt_pk_bf16_f32 v52, v58, v59
	v_cvt_pk_bf16_f32 v53, v60, v61
	v_max_f32_e32 v42, 0, v42
	v_max_f32_e32 v43, 0, v43
	global_store_dwordx4 v[62:63], v[50:53], off offset:256
	s_nop 1
	v_pk_mul_f32 v[52:53], v[42:43], v[42:43]
	v_add_u32_e32 v50, 0x90, v146
	v_max_f32_e32 v46, 0, v46
	v_max_f32_e32 v47, 0, v47
	v_max_f32_e32 v44, 0, v44
	v_ashrrev_i32_e32 v51, 31, v50
	v_pk_mul_f32 v[46:47], v[46:47], v[46:47]
	v_max_f32_e32 v42, 0, v48
	v_max_f32_e32 v43, 0, v49
	v_max_f32_e32 v45, 0, v45
	v_pk_mul_f32 v[48:49], v[42:43], v[42:43]
	v_cvt_pk_bf16_f32 v42, v46, v47
	v_lshlrev_b64 v[46:47], 13, v[50:51]
	v_pk_mul_f32 v[54:55], v[44:45], v[44:45]
	v_lshl_add_u64 v[46:47], s[42:43], 0, v[46:47]
	v_cvt_pk_bf16_f32 v43, v48, v49
	v_cvt_pk_bf16_f32 v44, v52, v53
	v_cvt_pk_bf16_f32 v45, v54, v55
	v_lshl_add_u64 v[46:47], v[46:47], 0, v[122:123]
	v_max_f32_e32 v34, 0, v34
	v_max_f32_e32 v35, 0, v35
	global_store_dwordx4 v[46:47], v[42:45], off
	s_nop 1
	v_pk_mul_f32 v[42:43], v[34:35], v[34:35]
	v_max_f32_e32 v36, 0, v36
	v_max_f32_e32 v38, 0, v38
	v_max_f32_e32 v39, 0, v39
	v_max_f32_e32 v34, 0, v40
	v_max_f32_e32 v35, 0, v41
	v_max_f32_e32 v37, 0, v37
	v_pk_mul_f32 v[38:39], v[38:39], v[38:39]
	v_pk_mul_f32 v[40:41], v[34:35], v[34:35]
	v_pk_mul_f32 v[44:45], v[36:37], v[36:37]
	v_cvt_pk_bf16_f32 v34, v38, v39
	v_cvt_pk_bf16_f32 v35, v40, v41
	v_cvt_pk_bf16_f32 v36, v42, v43
	v_cvt_pk_bf16_f32 v37, v44, v45
	v_max_f32_e32 v26, 0, v26
	v_max_f32_e32 v27, 0, v27
	global_store_dwordx4 v[46:47], v[34:37], off offset:256
	s_nop 1
	v_pk_mul_f32 v[36:37], v[26:27], v[26:27]
	v_add_u32_e32 v34, 0xa0, v146
	v_max_f32_e32 v30, 0, v30
	v_max_f32_e32 v31, 0, v31
	v_max_f32_e32 v28, 0, v28
	v_ashrrev_i32_e32 v35, 31, v34
	v_pk_mul_f32 v[30:31], v[30:31], v[30:31]
	v_max_f32_e32 v26, 0, v32
	v_max_f32_e32 v27, 0, v33
	v_max_f32_e32 v29, 0, v29
	v_pk_mul_f32 v[32:33], v[26:27], v[26:27]
	v_cvt_pk_bf16_f32 v26, v30, v31
	v_lshlrev_b64 v[30:31], 13, v[34:35]
	v_pk_mul_f32 v[38:39], v[28:29], v[28:29]
	v_lshl_add_u64 v[30:31], s[42:43], 0, v[30:31]
	v_cvt_pk_bf16_f32 v27, v32, v33
	v_cvt_pk_bf16_f32 v28, v36, v37
	v_cvt_pk_bf16_f32 v29, v38, v39
	v_lshl_add_u64 v[30:31], v[30:31], 0, v[122:123]
	v_max_f32_e32 v18, 0, v18
	v_max_f32_e32 v19, 0, v19
	global_store_dwordx4 v[30:31], v[26:29], off
	s_nop 1
	v_pk_mul_f32 v[26:27], v[18:19], v[18:19]
	v_max_f32_e32 v20, 0, v20
	v_max_f32_e32 v22, 0, v22
	v_max_f32_e32 v23, 0, v23
	v_max_f32_e32 v18, 0, v24
	v_max_f32_e32 v19, 0, v25
	v_max_f32_e32 v21, 0, v21
	v_pk_mul_f32 v[22:23], v[22:23], v[22:23]
	v_pk_mul_f32 v[24:25], v[18:19], v[18:19]
	v_pk_mul_f32 v[28:29], v[20:21], v[20:21]
	v_cvt_pk_bf16_f32 v18, v22, v23
	v_cvt_pk_bf16_f32 v19, v24, v25
	v_cvt_pk_bf16_f32 v20, v26, v27
	v_cvt_pk_bf16_f32 v21, v28, v29
	v_max_f32_e32 v10, 0, v10
	v_max_f32_e32 v11, 0, v11
	global_store_dwordx4 v[30:31], v[18:21], off offset:256
	s_nop 1
	v_pk_mul_f32 v[20:21], v[10:11], v[10:11]
	v_add_u32_e32 v18, 0xb0, v146
	v_max_f32_e32 v14, 0, v14
	v_max_f32_e32 v15, 0, v15
	v_max_f32_e32 v12, 0, v12
	v_ashrrev_i32_e32 v19, 31, v18
	v_pk_mul_f32 v[14:15], v[14:15], v[14:15]
	v_max_f32_e32 v10, 0, v16
	v_max_f32_e32 v11, 0, v17
	v_max_f32_e32 v13, 0, v13
	v_pk_mul_f32 v[16:17], v[10:11], v[10:11]
	v_cvt_pk_bf16_f32 v10, v14, v15
	v_lshlrev_b64 v[14:15], 13, v[18:19]
	v_pk_mul_f32 v[22:23], v[12:13], v[12:13]
	v_lshl_add_u64 v[14:15], s[42:43], 0, v[14:15]
	v_cvt_pk_bf16_f32 v11, v16, v17
	v_cvt_pk_bf16_f32 v12, v20, v21
	v_cvt_pk_bf16_f32 v13, v22, v23
	v_lshl_add_u64 v[14:15], v[14:15], 0, v[122:123]
	v_max_f32_e32 v2, 0, v2
	v_max_f32_e32 v3, 0, v3
	global_store_dwordx4 v[14:15], v[10:13], off
	s_nop 1
	v_pk_mul_f32 v[10:11], v[2:3], v[2:3]
	v_max_f32_e32 v4, 0, v4
	v_max_f32_e32 v6, 0, v6
	v_max_f32_e32 v7, 0, v7
	v_max_f32_e32 v2, 0, v8
	v_max_f32_e32 v3, 0, v9
	v_max_f32_e32 v5, 0, v5
	v_pk_mul_f32 v[6:7], v[6:7], v[6:7]
	v_pk_mul_f32 v[8:9], v[2:3], v[2:3]
	v_pk_mul_f32 v[12:13], v[4:5], v[4:5]
	v_cvt_pk_bf16_f32 v2, v6, v7
	v_cvt_pk_bf16_f32 v3, v8, v9
	v_cvt_pk_bf16_f32 v4, v10, v11
	v_cvt_pk_bf16_f32 v5, v12, v13
	s_andn2_b64 vcc, exec, s[4:5]
	s_mov_b64 s[4:5], -1
	global_store_dwordx4 v[14:15], v[2:5], off offset:256
	s_cbranch_vccnz .LBB0_741
	s_branch .LBB0_740

.LBB0_1619:
	ds_read_b128 v[154:157], v150
	ds_read_b128 v[158:161], v150 offset:1024
	ds_read_b128 v[162:165], v150 offset:2048
	ds_read_b128 v[166:169], v150 offset:3072
	ds_read_b128 v[170:173], v151
	ds_read_b128 v[174:177], v151 offset:1024
	ds_read_b128 v[178:181], v151 offset:2048
	ds_read_b128 v[182:185], v151 offset:3072
	s_add_u32 s30, s28, 0xfffc0080
	s_addc_u32 s31, s29, -1
	s_cmp_eq_u32 s62, 12
	s_cselect_b32 s37, s14, s31
	s_cselect_b32 s36, s15, s30
	s_cselect_b32 s31, s17, s51
	s_cselect_b32 s30, s49, s50
	v_lshl_add_u64 v[146:147], s[28:29], 0, v[138:139]
	s_add_i32 m0, s19, 0xc000
	ds_read_b128 v[186:189], v152
	ds_read_b128 v[190:193], v152 offset:1024
	ds_read_b128 v[194:197], v152 offset:2048
	ds_read_b128 v[198:201], v152 offset:3072
	ds_read_b128 v[206:209], v152 offset:4096
	ds_read_b128 v[210:213], v152 offset:5120
	ds_read_b128 v[214:217], v152 offset:6144
	ds_read_b128 v[218:221], v152 offset:7168
	global_load_lds_dwordx4 v[146:147], off
	v_lshl_add_u64 v[146:147], s[28:29], 0, v[140:141]
	s_add_i32 m0, s19, 0xe000
	s_nop 0
	global_load_lds_dwordx4 v[146:147], off
	s_waitcnt vmcnt(8)
	s_waitcnt lgkmcnt(0)
	s_barrier
	s_setprio 1
	s_waitcnt lgkmcnt(0)
	v_mfma_f32_16x16x32_bf16 v[126:129], v[154:157], v[186:189], v[126:129]
	v_mfma_f32_16x16x32_bf16 v[122:125], v[162:165], v[186:189], v[122:125]
	v_mfma_f32_16x16x32_bf16 v[110:113], v[154:157], v[194:197], v[110:113]
	v_mfma_f32_16x16x32_bf16 v[106:109], v[162:165], v[194:197], v[106:109]
	v_mfma_f32_16x16x32_bf16 v[94:97], v[154:157], v[206:209], v[94:97]
	v_mfma_f32_16x16x32_bf16 v[90:93], v[162:165], v[206:209], v[90:93]
	v_mfma_f32_16x16x32_bf16 v[78:81], v[154:157], v[214:217], v[78:81]
	v_mfma_f32_16x16x32_bf16 v[74:77], v[162:165], v[214:217], v[74:77]
	v_mfma_f32_16x16x32_bf16 v[126:129], v[158:161], v[190:193], v[126:129]
	v_mfma_f32_16x16x32_bf16 v[122:125], v[166:169], v[190:193], v[122:125]
	v_mfma_f32_16x16x32_bf16 v[110:113], v[158:161], v[198:201], v[110:113]
	v_mfma_f32_16x16x32_bf16 v[106:109], v[166:169], v[198:201], v[106:109]
	v_mfma_f32_16x16x32_bf16 v[94:97], v[158:161], v[210:213], v[94:97]
	v_mfma_f32_16x16x32_bf16 v[90:93], v[166:169], v[210:213], v[90:93]
	v_mfma_f32_16x16x32_bf16 v[78:81], v[158:161], v[218:221], v[78:81]
	v_mfma_f32_16x16x32_bf16 v[74:77], v[166:169], v[218:221], v[74:77]
	s_setprio 0
	s_setprio 1
	v_mfma_f32_16x16x32_bf16 v[118:121], v[170:173], v[186:189], v[118:121]
	v_mfma_f32_16x16x32_bf16 v[114:117], v[178:181], v[186:189], v[114:117]
	v_mfma_f32_16x16x32_bf16 v[102:105], v[170:173], v[194:197], v[102:105]
	v_mfma_f32_16x16x32_bf16 v[98:101], v[178:181], v[194:197], v[98:101]
	v_mfma_f32_16x16x32_bf16 v[86:89], v[170:173], v[206:209], v[86:89]
	v_mfma_f32_16x16x32_bf16 v[82:85], v[178:181], v[206:209], v[82:85]
	v_mfma_f32_16x16x32_bf16 v[70:73], v[170:173], v[214:217], v[70:73]
	v_mfma_f32_16x16x32_bf16 v[66:69], v[178:181], v[214:217], v[66:69]
	v_mfma_f32_16x16x32_bf16 v[118:121], v[174:177], v[190:193], v[118:121]
	v_mfma_f32_16x16x32_bf16 v[114:117], v[182:185], v[190:193], v[114:117]
	v_mfma_f32_16x16x32_bf16 v[102:105], v[174:177], v[198:201], v[102:105]
	v_mfma_f32_16x16x32_bf16 v[98:101], v[182:185], v[198:201], v[98:101]
	v_mfma_f32_16x16x32_bf16 v[86:89], v[174:177], v[210:213], v[86:89]
	v_mfma_f32_16x16x32_bf16 v[82:85], v[182:185], v[210:213], v[82:85]
	v_mfma_f32_16x16x32_bf16 v[70:73], v[174:177], v[218:221], v[70:73]
	v_mfma_f32_16x16x32_bf16 v[66:69], v[182:185], v[218:221], v[66:69]
	s_setprio 0
	s_barrier
	s_add_i32 s63, s45, s12
	v_lshl_add_u64 v[146:147], s[30:31], 0, v[134:135]
	s_mov_b32 m0, s63
	ds_read_b128 v[186:189], v152 offset:16384
	ds_read_b128 v[190:193], v152 offset:17408
	ds_read_b128 v[194:197], v152 offset:18432
	ds_read_b128 v[198:201], v152 offset:19456
	ds_read_b128 v[206:209], v152 offset:20480
	ds_read_b128 v[210:213], v152 offset:21504
	ds_read_b128 v[214:217], v152 offset:22528
	ds_read_b128 v[218:221], v152 offset:23552
	global_load_lds_dwordx4 v[146:147], off
	s_add_i32 m0, s63, 0x2000
	s_add_u32 s64, s30, 0x40000
	v_lshl_add_u64 v[202:203], s[30:31], 0, v[130:131]
	s_addc_u32 s65, s31, 0
	s_add_i32 s63, s46, s12
	global_load_lds_dwordx4 v[202:203], off
	v_lshl_add_u64 v[222:223], s[64:65], 0, v[134:135]
	s_mov_b32 m0, s63
	v_lshl_add_u64 v[224:225], s[36:37], 0, v[132:133]
	global_load_lds_dwordx4 v[222:223], off
	v_lshl_add_u64 v[222:223], s[64:65], 0, v[130:131]
	s_add_i32 m0, s63, 0x2000
	s_nop 0
	global_load_lds_dwordx4 v[222:223], off
	v_lshl_add_u64 v[222:223], s[36:37], 0, v[136:137]
	s_mov_b32 m0, s19
	s_nop 0
	global_load_lds_dwordx4 v[222:223], off
	s_mov_b32 m0, s33
	s_nop 0
	global_load_lds_dwordx4 v[224:225], off
	s_waitcnt vmcnt(8)
	s_waitcnt lgkmcnt(0)
	s_barrier
	s_setprio 1
	s_waitcnt lgkmcnt(0)
	v_mfma_f32_16x16x32_bf16 v[62:65], v[154:157], v[186:189], v[62:65]
	v_mfma_f32_16x16x32_bf16 v[58:61], v[162:165], v[186:189], v[58:61]
	v_mfma_f32_16x16x32_bf16 v[46:49], v[154:157], v[194:197], v[46:49]
	v_mfma_f32_16x16x32_bf16 v[42:45], v[162:165], v[194:197], v[42:45]
	v_mfma_f32_16x16x32_bf16 v[30:33], v[154:157], v[206:209], v[30:33]
	v_mfma_f32_16x16x32_bf16 v[26:29], v[162:165], v[206:209], v[26:29]
	v_mfma_f32_16x16x32_bf16 v[14:17], v[154:157], v[214:217], v[14:17]
	v_mfma_f32_16x16x32_bf16 v[10:13], v[162:165], v[214:217], v[10:13]
	v_mfma_f32_16x16x32_bf16 v[62:65], v[158:161], v[190:193], v[62:65]
	v_mfma_f32_16x16x32_bf16 v[58:61], v[166:169], v[190:193], v[58:61]
	v_mfma_f32_16x16x32_bf16 v[46:49], v[158:161], v[198:201], v[46:49]
	v_mfma_f32_16x16x32_bf16 v[42:45], v[166:169], v[198:201], v[42:45]
	v_mfma_f32_16x16x32_bf16 v[30:33], v[158:161], v[210:213], v[30:33]
	v_mfma_f32_16x16x32_bf16 v[26:29], v[166:169], v[210:213], v[26:29]
	v_mfma_f32_16x16x32_bf16 v[14:17], v[158:161], v[218:221], v[14:17]
	v_mfma_f32_16x16x32_bf16 v[10:13], v[166:169], v[218:221], v[10:13]
	s_setprio 0
	s_setprio 1
	v_mfma_f32_16x16x32_bf16 v[54:57], v[170:173], v[186:189], v[54:57]
	v_mfma_f32_16x16x32_bf16 v[50:53], v[178:181], v[186:189], v[50:53]
	v_mfma_f32_16x16x32_bf16 v[38:41], v[170:173], v[194:197], v[38:41]
	v_mfma_f32_16x16x32_bf16 v[34:37], v[178:181], v[194:197], v[34:37]
	v_mfma_f32_16x16x32_bf16 v[22:25], v[170:173], v[206:209], v[22:25]
	v_mfma_f32_16x16x32_bf16 v[18:21], v[178:181], v[206:209], v[18:21]
	v_mfma_f32_16x16x32_bf16 v[6:9], v[170:173], v[214:217], v[6:9]
	v_mfma_f32_16x16x32_bf16 v[2:5], v[178:181], v[214:217], v[2:5]
	v_mfma_f32_16x16x32_bf16 v[54:57], v[174:177], v[190:193], v[54:57]
	v_mfma_f32_16x16x32_bf16 v[50:53], v[182:185], v[190:193], v[50:53]
	v_mfma_f32_16x16x32_bf16 v[38:41], v[174:177], v[198:201], v[38:41]
	v_mfma_f32_16x16x32_bf16 v[34:37], v[182:185], v[198:201], v[34:37]
	v_mfma_f32_16x16x32_bf16 v[22:25], v[174:177], v[210:213], v[22:25]
	v_mfma_f32_16x16x32_bf16 v[18:21], v[182:185], v[210:213], v[18:21]
	v_mfma_f32_16x16x32_bf16 v[6:9], v[174:177], v[218:221], v[6:9]
	v_mfma_f32_16x16x32_bf16 v[2:5], v[182:185], v[218:221], v[2:5]
	s_setprio 0
	s_barrier
	s_add_i32 s63, 0, 0x18000
	v_add_u32_e32 v153, s63, v149
	s_add_i32 s64, 0, 0x1c000
	ds_read_b128 v[154:157], v153
	ds_read_b128 v[158:161], v153 offset:1024
	ds_read_b128 v[162:165], v153 offset:2048
	ds_read_b128 v[166:169], v153 offset:3072
	v_add_u32_e32 v153, s64, v149
	ds_read_b128 v[170:173], v153
	ds_read_b128 v[174:177], v153 offset:1024
	ds_read_b128 v[178:181], v153 offset:2048
	ds_read_b128 v[182:185], v153 offset:3072
	s_add_u32 s36, s36, 0x40000
	s_addc_u32 s37, s37, 0
	s_mov_b32 m0, s35
	v_lshl_add_u64 v[226:227], s[36:37], 0, v[136:137]
	ds_read_b128 v[186:189], v152 offset:32768
	ds_read_b128 v[190:193], v152 offset:33792
	ds_read_b128 v[194:197], v152 offset:34816
	ds_read_b128 v[198:201], v152 offset:35840
	ds_read_b128 v[206:209], v152 offset:36864
	ds_read_b128 v[210:213], v152 offset:37888
	ds_read_b128 v[214:217], v152 offset:38912
	ds_read_b128 v[218:221], v152 offset:39936
	global_load_lds_dwordx4 v[226:227], off
	v_lshl_add_u64 v[226:227], s[36:37], 0, v[132:133]
	s_mov_b32 m0, s38
	s_nop 0
	global_load_lds_dwordx4 v[226:227], off
	s_waitcnt vmcnt(8)
	s_waitcnt lgkmcnt(0)
	s_barrier
	s_setprio 1
	s_waitcnt lgkmcnt(0)
	v_mfma_f32_16x16x32_bf16 v[126:129], v[154:157], v[186:189], v[126:129]
	v_mfma_f32_16x16x32_bf16 v[122:125], v[162:165], v[186:189], v[122:125]
	v_mfma_f32_16x16x32_bf16 v[110:113], v[154:157], v[194:197], v[110:113]
	v_mfma_f32_16x16x32_bf16 v[106:109], v[162:165], v[194:197], v[106:109]
	v_mfma_f32_16x16x32_bf16 v[94:97], v[154:157], v[206:209], v[94:97]
	v_mfma_f32_16x16x32_bf16 v[90:93], v[162:165], v[206:209], v[90:93]
	v_mfma_f32_16x16x32_bf16 v[78:81], v[154:157], v[214:217], v[78:81]
	v_mfma_f32_16x16x32_bf16 v[74:77], v[162:165], v[214:217], v[74:77]
	v_mfma_f32_16x16x32_bf16 v[126:129], v[158:161], v[190:193], v[126:129]
	v_mfma_f32_16x16x32_bf16 v[122:125], v[166:169], v[190:193], v[122:125]
	v_mfma_f32_16x16x32_bf16 v[110:113], v[158:161], v[198:201], v[110:113]
	v_mfma_f32_16x16x32_bf16 v[106:109], v[166:169], v[198:201], v[106:109]
	v_mfma_f32_16x16x32_bf16 v[94:97], v[158:161], v[210:213], v[94:97]
	v_mfma_f32_16x16x32_bf16 v[90:93], v[166:169], v[210:213], v[90:93]
	v_mfma_f32_16x16x32_bf16 v[78:81], v[158:161], v[218:221], v[78:81]
	v_mfma_f32_16x16x32_bf16 v[74:77], v[166:169], v[218:221], v[74:77]
	s_setprio 0
	s_setprio 1
	v_mfma_f32_16x16x32_bf16 v[118:121], v[170:173], v[186:189], v[118:121]
	v_mfma_f32_16x16x32_bf16 v[114:117], v[178:181], v[186:189], v[114:117]
	v_mfma_f32_16x16x32_bf16 v[102:105], v[170:173], v[194:197], v[102:105]
	v_mfma_f32_16x16x32_bf16 v[98:101], v[178:181], v[194:197], v[98:101]
	v_mfma_f32_16x16x32_bf16 v[86:89], v[170:173], v[206:209], v[86:89]
	v_mfma_f32_16x16x32_bf16 v[82:85], v[178:181], v[206:209], v[82:85]
	v_mfma_f32_16x16x32_bf16 v[70:73], v[170:173], v[214:217], v[70:73]
	v_mfma_f32_16x16x32_bf16 v[66:69], v[178:181], v[214:217], v[66:69]
	v_mfma_f32_16x16x32_bf16 v[118:121], v[174:177], v[190:193], v[118:121]
	v_mfma_f32_16x16x32_bf16 v[114:117], v[182:185], v[190:193], v[114:117]
	v_mfma_f32_16x16x32_bf16 v[102:105], v[174:177], v[198:201], v[102:105]
	v_mfma_f32_16x16x32_bf16 v[98:101], v[182:185], v[198:201], v[98:101]
	v_mfma_f32_16x16x32_bf16 v[86:89], v[174:177], v[210:213], v[86:89]
	v_mfma_f32_16x16x32_bf16 v[82:85], v[182:185], v[210:213], v[82:85]
	v_mfma_f32_16x16x32_bf16 v[70:73], v[174:177], v[218:221], v[70:73]
	v_mfma_f32_16x16x32_bf16 v[66:69], v[182:185], v[218:221], v[66:69]
	s_setprio 0
	s_barrier
	s_add_i32 s36, s63, s12
	v_lshl_add_u64 v[146:147], v[146:147], 0, s[8:9]
	s_mov_b32 m0, s36
	ds_read_b128 v[186:189], v152 offset:49152
	ds_read_b128 v[190:193], v152 offset:50176
	ds_read_b128 v[194:197], v152 offset:51200
	ds_read_b128 v[198:201], v152 offset:52224
	ds_read_b128 v[206:209], v152 offset:53248
	ds_read_b128 v[210:213], v152 offset:54272
	ds_read_b128 v[214:217], v152 offset:55296
	ds_read_b128 v[218:221], v152 offset:56320
	global_load_lds_dwordx4 v[146:147], off
	s_add_i32 m0, s36, 0x2000
	s_add_u32 s30, s30, 0x40080
	v_lshl_add_u64 v[146:147], v[202:203], 0, s[8:9]
	s_addc_u32 s31, s31, 0
	s_add_i32 s36, s64, s12
	global_load_lds_dwordx4 v[146:147], off
	v_lshl_add_u64 v[146:147], s[30:31], 0, v[134:135]
	s_mov_b32 m0, s36
	s_nop 0
	global_load_lds_dwordx4 v[146:147], off
	v_lshl_add_u64 v[146:147], s[30:31], 0, v[130:131]
	s_add_i32 m0, s36, 0x2000
	s_nop 0
	global_load_lds_dwordx4 v[146:147], off
	v_lshl_add_u64 v[146:147], v[222:223], 0, s[8:9]
	s_mov_b32 m0, s42
	s_nop 0
	global_load_lds_dwordx4 v[146:147], off
	v_lshl_add_u64 v[146:147], v[224:225], 0, s[8:9]
	s_mov_b32 m0, s43
	s_nop 0
	global_load_lds_dwordx4 v[146:147], off
	s_waitcnt vmcnt(8)
	s_waitcnt lgkmcnt(0)
	s_barrier
	s_setprio 1
	s_waitcnt lgkmcnt(0)
	v_mfma_f32_16x16x32_bf16 v[62:65], v[154:157], v[186:189], v[62:65]
	v_mfma_f32_16x16x32_bf16 v[58:61], v[162:165], v[186:189], v[58:61]
	v_mfma_f32_16x16x32_bf16 v[46:49], v[154:157], v[194:197], v[46:49]
	v_mfma_f32_16x16x32_bf16 v[42:45], v[162:165], v[194:197], v[42:45]
	v_mfma_f32_16x16x32_bf16 v[30:33], v[154:157], v[206:209], v[30:33]
	v_mfma_f32_16x16x32_bf16 v[26:29], v[162:165], v[206:209], v[26:29]
	v_mfma_f32_16x16x32_bf16 v[14:17], v[154:157], v[214:217], v[14:17]
	v_mfma_f32_16x16x32_bf16 v[10:13], v[162:165], v[214:217], v[10:13]
	v_mfma_f32_16x16x32_bf16 v[62:65], v[158:161], v[190:193], v[62:65]
	v_mfma_f32_16x16x32_bf16 v[58:61], v[166:169], v[190:193], v[58:61]
	v_mfma_f32_16x16x32_bf16 v[46:49], v[158:161], v[198:201], v[46:49]
	v_mfma_f32_16x16x32_bf16 v[42:45], v[166:169], v[198:201], v[42:45]
	v_mfma_f32_16x16x32_bf16 v[30:33], v[158:161], v[210:213], v[30:33]
	v_mfma_f32_16x16x32_bf16 v[26:29], v[166:169], v[210:213], v[26:29]
	v_mfma_f32_16x16x32_bf16 v[14:17], v[158:161], v[218:221], v[14:17]
	v_mfma_f32_16x16x32_bf16 v[10:13], v[166:169], v[218:221], v[10:13]
	s_setprio 0
	s_setprio 1
	v_mfma_f32_16x16x32_bf16 v[54:57], v[170:173], v[186:189], v[54:57]
	v_mfma_f32_16x16x32_bf16 v[50:53], v[178:181], v[186:189], v[50:53]
	v_mfma_f32_16x16x32_bf16 v[38:41], v[170:173], v[194:197], v[38:41]
	v_mfma_f32_16x16x32_bf16 v[34:37], v[178:181], v[194:197], v[34:37]
	v_mfma_f32_16x16x32_bf16 v[22:25], v[170:173], v[206:209], v[22:25]
	v_mfma_f32_16x16x32_bf16 v[18:21], v[178:181], v[206:209], v[18:21]
	v_mfma_f32_16x16x32_bf16 v[6:9], v[170:173], v[214:217], v[6:9]
	v_mfma_f32_16x16x32_bf16 v[2:5], v[178:181], v[214:217], v[2:5]
	v_mfma_f32_16x16x32_bf16 v[54:57], v[174:177], v[190:193], v[54:57]
	v_mfma_f32_16x16x32_bf16 v[50:53], v[182:185], v[190:193], v[50:53]
	v_mfma_f32_16x16x32_bf16 v[38:41], v[174:177], v[198:201], v[38:41]
	v_mfma_f32_16x16x32_bf16 v[34:37], v[182:185], v[198:201], v[34:37]
	v_mfma_f32_16x16x32_bf16 v[22:25], v[174:177], v[210:213], v[22:25]
	v_mfma_f32_16x16x32_bf16 v[18:21], v[182:185], v[210:213], v[18:21]
	v_mfma_f32_16x16x32_bf16 v[6:9], v[174:177], v[218:221], v[6:9]
	v_mfma_f32_16x16x32_bf16 v[2:5], v[182:185], v[218:221], v[2:5]
	s_setprio 0
	s_barrier
	s_add_i32 s62, s62, 2
	s_add_u32 s28, s28, 0x100
	s_addc_u32 s29, s29, 0
	s_add_u32 s50, s50, 0x100
	s_addc_u32 s51, s51, 0
	s_cmp_gt_u32 s62, 13
	s_cbranch_scc0 .LBB0_1619
	s_cmp_lg_u64 s[4:5], 0
	s_cbranch_scc1 .LBB0_1622
	s_and_b64 vcc, exec, s[10:11]
	s_cbranch_vccz .LBB0_1622
	s_barrier
.LBB0_1622:
	s_lshl_b32 s14, s34, 8
	s_ashr_i32 s15, s14, 31
	s_lshl_b64 s[14:15], s[14:15], 13
	v_readlane_b32 s28, v249, 32
	v_readlane_b32 s29, v249, 33
	s_add_u32 s17, s28, s14
	s_addc_u32 s29, s29, s15
	s_lshl_b32 s14, s48, 8
	v_mov_b32_e32 v146, v1
	v_mov_b32_e32 v147, v148
	s_ashr_i32 s15, s14, 31
	s_lshl_b64 s[14:15], s[14:15], 1
	v_add_u32_e32 v146, s40, v146
	v_max_f32_e32 v126, 0, v126
	v_max_f32_e32 v122, 0, v122
	v_max_f32_e32 v127, 0, v127
	v_max_f32_e32 v123, 0, v123
	s_add_u32 s28, s17, s14
	v_lshl_add_u32 v154, v147, 3, s41
	v_ashrrev_i32_e32 v147, 31, v146
	v_pk_mul_f32 v[126:127], v[126:127], v[126:127]
	v_pk_mul_f32 v[122:123], v[122:123], v[122:123]
	v_max_f32_e32 v128, 0, v128
	v_max_f32_e32 v124, 0, v124
	v_max_f32_e32 v129, 0, v129
	v_max_f32_e32 v125, 0, v125
	s_addc_u32 s29, s29, s15
	v_pk_mul_f32 v[128:129], v[128:129], v[128:129]
	v_pk_mul_f32 v[156:157], v[124:125], v[124:125]
	v_cvt_pk_bf16_f32 v124, v126, v127
	v_cvt_pk_bf16_f32 v126, v122, v123
	v_lshlrev_b64 v[122:123], 13, v[146:147]
	v_ashrrev_i32_e32 v155, 31, v154
	v_cvt_pk_bf16_f32 v125, v128, v129
	v_lshl_add_u64 v[128:129], s[28:29], 0, v[122:123]
	v_lshlrev_b64 v[122:123], 1, v[154:155]
	v_cvt_pk_bf16_f32 v127, v156, v157
	v_lshl_add_u64 v[128:129], v[128:129], 0, v[122:123]
	v_max_f32_e32 v114, 0, v114
	v_max_f32_e32 v115, 0, v115
	global_store_dwordx4 v[128:129], v[124:127], off
	s_nop 1
	v_pk_mul_f32 v[124:125], v[114:115], v[114:115]
	v_max_f32_e32 v116, 0, v116
	v_max_f32_e32 v118, 0, v118
	v_max_f32_e32 v119, 0, v119
	v_max_f32_e32 v114, 0, v120
	v_max_f32_e32 v115, 0, v121
	v_max_f32_e32 v117, 0, v117
	v_pk_mul_f32 v[118:119], v[118:119], v[118:119]
	v_pk_mul_f32 v[120:121], v[114:115], v[114:115]
	v_pk_mul_f32 v[126:127], v[116:117], v[116:117]
	v_cvt_pk_bf16_f32 v114, v118, v119
	v_cvt_pk_bf16_f32 v115, v120, v121
	v_cvt_pk_bf16_f32 v116, v124, v125
	v_cvt_pk_bf16_f32 v117, v126, v127
	v_max_f32_e32 v106, 0, v106
	v_max_f32_e32 v107, 0, v107
	global_store_dwordx4 v[128:129], v[114:117], off offset:256
	s_nop 1
	v_pk_mul_f32 v[116:117], v[106:107], v[106:107]
	v_add_u32_e32 v114, 16, v146
	v_max_f32_e32 v110, 0, v110
	v_max_f32_e32 v111, 0, v111
	v_max_f32_e32 v108, 0, v108
	v_ashrrev_i32_e32 v115, 31, v114
	v_pk_mul_f32 v[110:111], v[110:111], v[110:111]
	v_max_f32_e32 v106, 0, v112
	v_max_f32_e32 v107, 0, v113
	v_max_f32_e32 v109, 0, v109
	v_pk_mul_f32 v[112:113], v[106:107], v[106:107]
	v_cvt_pk_bf16_f32 v106, v110, v111
	v_lshlrev_b64 v[110:111], 13, v[114:115]
	v_pk_mul_f32 v[118:119], v[108:109], v[108:109]
	v_lshl_add_u64 v[110:111], s[28:29], 0, v[110:111]
	v_cvt_pk_bf16_f32 v107, v112, v113
	v_cvt_pk_bf16_f32 v108, v116, v117
	v_cvt_pk_bf16_f32 v109, v118, v119
	v_lshl_add_u64 v[110:111], v[110:111], 0, v[122:123]
	v_max_f32_e32 v98, 0, v98
	v_max_f32_e32 v99, 0, v99
	global_store_dwordx4 v[110:111], v[106:109], off
	s_nop 1
	v_pk_mul_f32 v[106:107], v[98:99], v[98:99]
	v_max_f32_e32 v100, 0, v100
	v_max_f32_e32 v102, 0, v102
	v_max_f32_e32 v103, 0, v103
	v_max_f32_e32 v98, 0, v104
	v_max_f32_e32 v99, 0, v105
	v_max_f32_e32 v101, 0, v101
	v_pk_mul_f32 v[102:103], v[102:103], v[102:103]
	v_pk_mul_f32 v[104:105], v[98:99], v[98:99]
	v_pk_mul_f32 v[108:109], v[100:101], v[100:101]
	v_cvt_pk_bf16_f32 v98, v102, v103
	v_cvt_pk_bf16_f32 v99, v104, v105
	v_cvt_pk_bf16_f32 v100, v106, v107
	v_cvt_pk_bf16_f32 v101, v108, v109
	v_max_f32_e32 v90, 0, v90
	v_max_f32_e32 v91, 0, v91
	global_store_dwordx4 v[110:111], v[98:101], off offset:256
	s_nop 1
	v_pk_mul_f32 v[100:101], v[90:91], v[90:91]
	v_add_u32_e32 v98, 32, v146
	v_max_f32_e32 v94, 0, v94
	v_max_f32_e32 v95, 0, v95
	v_max_f32_e32 v92, 0, v92
	v_ashrrev_i32_e32 v99, 31, v98
	v_pk_mul_f32 v[94:95], v[94:95], v[94:95]
	v_max_f32_e32 v90, 0, v96
	v_max_f32_e32 v91, 0, v97
	v_max_f32_e32 v93, 0, v93
	v_pk_mul_f32 v[96:97], v[90:91], v[90:91]
	v_cvt_pk_bf16_f32 v90, v94, v95
	v_lshlrev_b64 v[94:95], 13, v[98:99]
	v_pk_mul_f32 v[102:103], v[92:93], v[92:93]
	v_lshl_add_u64 v[94:95], s[28:29], 0, v[94:95]
	v_cvt_pk_bf16_f32 v91, v96, v97
	v_cvt_pk_bf16_f32 v92, v100, v101
	v_cvt_pk_bf16_f32 v93, v102, v103
	v_lshl_add_u64 v[94:95], v[94:95], 0, v[122:123]
	v_max_f32_e32 v82, 0, v82
	v_max_f32_e32 v83, 0, v83
	global_store_dwordx4 v[94:95], v[90:93], off
	s_nop 1
	v_pk_mul_f32 v[90:91], v[82:83], v[82:83]
	v_max_f32_e32 v84, 0, v84
	v_max_f32_e32 v86, 0, v86
	v_max_f32_e32 v87, 0, v87
	v_max_f32_e32 v82, 0, v88
	v_max_f32_e32 v83, 0, v89
	v_max_f32_e32 v85, 0, v85
	v_pk_mul_f32 v[86:87], v[86:87], v[86:87]
	v_pk_mul_f32 v[88:89], v[82:83], v[82:83]
	v_pk_mul_f32 v[92:93], v[84:85], v[84:85]
	v_cvt_pk_bf16_f32 v82, v86, v87
	v_cvt_pk_bf16_f32 v83, v88, v89
	v_cvt_pk_bf16_f32 v84, v90, v91
	v_cvt_pk_bf16_f32 v85, v92, v93
	v_max_f32_e32 v74, 0, v74
	v_max_f32_e32 v75, 0, v75
	global_store_dwordx4 v[94:95], v[82:85], off offset:256
	s_nop 1
	v_pk_mul_f32 v[84:85], v[74:75], v[74:75]
	v_add_u32_e32 v82, 48, v146
	v_max_f32_e32 v78, 0, v78
	v_max_f32_e32 v79, 0, v79
	v_max_f32_e32 v76, 0, v76
	v_ashrrev_i32_e32 v83, 31, v82
	v_pk_mul_f32 v[78:79], v[78:79], v[78:79]
	v_max_f32_e32 v74, 0, v80
	v_max_f32_e32 v75, 0, v81
	v_max_f32_e32 v77, 0, v77
	v_pk_mul_f32 v[80:81], v[74:75], v[74:75]
	v_cvt_pk_bf16_f32 v74, v78, v79
	v_lshlrev_b64 v[78:79], 13, v[82:83]
	v_pk_mul_f32 v[86:87], v[76:77], v[76:77]
	v_lshl_add_u64 v[78:79], s[28:29], 0, v[78:79]
	v_cvt_pk_bf16_f32 v75, v80, v81
	v_cvt_pk_bf16_f32 v76, v84, v85
	v_cvt_pk_bf16_f32 v77, v86, v87
	v_lshl_add_u64 v[78:79], v[78:79], 0, v[122:123]
	v_max_f32_e32 v66, 0, v66
	v_max_f32_e32 v67, 0, v67
	global_store_dwordx4 v[78:79], v[74:77], off
	s_nop 1
	v_pk_mul_f32 v[74:75], v[66:67], v[66:67]
	v_max_f32_e32 v68, 0, v68
	v_max_f32_e32 v70, 0, v70
	v_max_f32_e32 v71, 0, v71
	v_max_f32_e32 v66, 0, v72
	v_max_f32_e32 v67, 0, v73
	v_max_f32_e32 v69, 0, v69
	v_pk_mul_f32 v[70:71], v[70:71], v[70:71]
	v_pk_mul_f32 v[72:73], v[66:67], v[66:67]
	v_pk_mul_f32 v[76:77], v[68:69], v[68:69]
	v_cvt_pk_bf16_f32 v66, v70, v71
	v_cvt_pk_bf16_f32 v67, v72, v73
	v_cvt_pk_bf16_f32 v68, v74, v75
	v_cvt_pk_bf16_f32 v69, v76, v77
	v_max_f32_e32 v58, 0, v58
	v_max_f32_e32 v59, 0, v59
	global_store_dwordx4 v[78:79], v[66:69], off offset:256
	s_nop 1
	v_pk_mul_f32 v[68:69], v[58:59], v[58:59]
	v_add_u32_e32 v66, 0x80, v146
	v_max_f32_e32 v62, 0, v62
	v_max_f32_e32 v63, 0, v63
	v_max_f32_e32 v60, 0, v60
	v_ashrrev_i32_e32 v67, 31, v66
	v_pk_mul_f32 v[62:63], v[62:63], v[62:63]
	v_max_f32_e32 v58, 0, v64
	v_max_f32_e32 v59, 0, v65
	v_max_f32_e32 v61, 0, v61
	v_pk_mul_f32 v[64:65], v[58:59], v[58:59]
	v_cvt_pk_bf16_f32 v58, v62, v63
	v_lshlrev_b64 v[62:63], 13, v[66:67]
	v_pk_mul_f32 v[70:71], v[60:61], v[60:61]
	v_lshl_add_u64 v[62:63], s[28:29], 0, v[62:63]
	v_cvt_pk_bf16_f32 v59, v64, v65
	v_cvt_pk_bf16_f32 v60, v68, v69
	v_cvt_pk_bf16_f32 v61, v70, v71
	v_lshl_add_u64 v[62:63], v[62:63], 0, v[122:123]
	v_max_f32_e32 v50, 0, v50
	v_max_f32_e32 v51, 0, v51
	global_store_dwordx4 v[62:63], v[58:61], off
	s_nop 1
	v_pk_mul_f32 v[58:59], v[50:51], v[50:51]
	v_max_f32_e32 v52, 0, v52
	v_max_f32_e32 v54, 0, v54
	v_max_f32_e32 v55, 0, v55
	v_max_f32_e32 v50, 0, v56
	v_max_f32_e32 v51, 0, v57
	v_max_f32_e32 v53, 0, v53
	v_pk_mul_f32 v[54:55], v[54:55], v[54:55]
	v_pk_mul_f32 v[56:57], v[50:51], v[50:51]
	v_pk_mul_f32 v[60:61], v[52:53], v[52:53]
	v_cvt_pk_bf16_f32 v50, v54, v55
	v_cvt_pk_bf16_f32 v51, v56, v57
	v_cvt_pk_bf16_f32 v52, v58, v59
	v_cvt_pk_bf16_f32 v53, v60, v61
	v_max_f32_e32 v42, 0, v42
	v_max_f32_e32 v43, 0, v43
	global_store_dwordx4 v[62:63], v[50:53], off offset:256
	s_nop 1
	v_pk_mul_f32 v[52:53], v[42:43], v[42:43]
	v_add_u32_e32 v50, 0x90, v146
	v_max_f32_e32 v46, 0, v46
	v_max_f32_e32 v47, 0, v47
	v_max_f32_e32 v44, 0, v44
	v_ashrrev_i32_e32 v51, 31, v50
	v_pk_mul_f32 v[46:47], v[46:47], v[46:47]
	v_max_f32_e32 v42, 0, v48
	v_max_f32_e32 v43, 0, v49
	v_max_f32_e32 v45, 0, v45
	v_pk_mul_f32 v[48:49], v[42:43], v[42:43]
	v_cvt_pk_bf16_f32 v42, v46, v47
	v_lshlrev_b64 v[46:47], 13, v[50:51]
	v_pk_mul_f32 v[54:55], v[44:45], v[44:45]
	v_lshl_add_u64 v[46:47], s[28:29], 0, v[46:47]
	v_cvt_pk_bf16_f32 v43, v48, v49
	v_cvt_pk_bf16_f32 v44, v52, v53
	v_cvt_pk_bf16_f32 v45, v54, v55
	v_lshl_add_u64 v[46:47], v[46:47], 0, v[122:123]
	v_max_f32_e32 v34, 0, v34
	v_max_f32_e32 v35, 0, v35
	global_store_dwordx4 v[46:47], v[42:45], off
	s_nop 1
	v_pk_mul_f32 v[42:43], v[34:35], v[34:35]
	v_max_f32_e32 v36, 0, v36
	v_max_f32_e32 v38, 0, v38
	v_max_f32_e32 v39, 0, v39
	v_max_f32_e32 v34, 0, v40
	v_max_f32_e32 v35, 0, v41
	v_max_f32_e32 v37, 0, v37
	v_pk_mul_f32 v[38:39], v[38:39], v[38:39]
	v_pk_mul_f32 v[40:41], v[34:35], v[34:35]
	v_pk_mul_f32 v[44:45], v[36:37], v[36:37]
	v_cvt_pk_bf16_f32 v34, v38, v39
	v_cvt_pk_bf16_f32 v35, v40, v41
	v_cvt_pk_bf16_f32 v36, v42, v43
	v_cvt_pk_bf16_f32 v37, v44, v45
	v_max_f32_e32 v26, 0, v26
	v_max_f32_e32 v27, 0, v27
	global_store_dwordx4 v[46:47], v[34:37], off offset:256
	s_nop 1
	v_pk_mul_f32 v[36:37], v[26:27], v[26:27]
	v_add_u32_e32 v34, 0xa0, v146
	v_max_f32_e32 v30, 0, v30
	v_max_f32_e32 v31, 0, v31
	v_max_f32_e32 v28, 0, v28
	v_ashrrev_i32_e32 v35, 31, v34
	v_pk_mul_f32 v[30:31], v[30:31], v[30:31]
	v_max_f32_e32 v26, 0, v32
	v_max_f32_e32 v27, 0, v33
	v_max_f32_e32 v29, 0, v29
	v_pk_mul_f32 v[32:33], v[26:27], v[26:27]
	v_cvt_pk_bf16_f32 v26, v30, v31
	v_lshlrev_b64 v[30:31], 13, v[34:35]
	v_pk_mul_f32 v[38:39], v[28:29], v[28:29]
	v_lshl_add_u64 v[30:31], s[28:29], 0, v[30:31]
	v_cvt_pk_bf16_f32 v27, v32, v33
	v_cvt_pk_bf16_f32 v28, v36, v37
	v_cvt_pk_bf16_f32 v29, v38, v39
	v_lshl_add_u64 v[30:31], v[30:31], 0, v[122:123]
	v_max_f32_e32 v18, 0, v18
	v_max_f32_e32 v19, 0, v19
	global_store_dwordx4 v[30:31], v[26:29], off
	s_nop 1
	v_pk_mul_f32 v[26:27], v[18:19], v[18:19]
	v_max_f32_e32 v20, 0, v20
	v_max_f32_e32 v22, 0, v22
	v_max_f32_e32 v23, 0, v23
	v_max_f32_e32 v18, 0, v24
	v_max_f32_e32 v19, 0, v25
	v_max_f32_e32 v21, 0, v21
	v_pk_mul_f32 v[22:23], v[22:23], v[22:23]
	v_pk_mul_f32 v[24:25], v[18:19], v[18:19]
	v_pk_mul_f32 v[28:29], v[20:21], v[20:21]
	v_cvt_pk_bf16_f32 v18, v22, v23
	v_cvt_pk_bf16_f32 v19, v24, v25
	v_cvt_pk_bf16_f32 v20, v26, v27
	v_cvt_pk_bf16_f32 v21, v28, v29
	v_max_f32_e32 v10, 0, v10
	v_max_f32_e32 v11, 0, v11
	global_store_dwordx4 v[30:31], v[18:21], off offset:256
	s_nop 1
	v_pk_mul_f32 v[20:21], v[10:11], v[10:11]
	v_add_u32_e32 v18, 0xb0, v146
	v_max_f32_e32 v14, 0, v14
	v_max_f32_e32 v15, 0, v15
	v_max_f32_e32 v12, 0, v12
	v_ashrrev_i32_e32 v19, 31, v18
	v_pk_mul_f32 v[14:15], v[14:15], v[14:15]
	v_max_f32_e32 v10, 0, v16
	v_max_f32_e32 v11, 0, v17
	v_max_f32_e32 v13, 0, v13
	v_pk_mul_f32 v[16:17], v[10:11], v[10:11]
	v_cvt_pk_bf16_f32 v10, v14, v15
	v_lshlrev_b64 v[14:15], 13, v[18:19]
	v_pk_mul_f32 v[22:23], v[12:13], v[12:13]
	v_lshl_add_u64 v[14:15], s[28:29], 0, v[14:15]
	v_cvt_pk_bf16_f32 v11, v16, v17
	v_cvt_pk_bf16_f32 v12, v20, v21
	v_cvt_pk_bf16_f32 v13, v22, v23
	v_lshl_add_u64 v[14:15], v[14:15], 0, v[122:123]
	v_max_f32_e32 v2, 0, v2
	v_max_f32_e32 v3, 0, v3
	global_store_dwordx4 v[14:15], v[10:13], off
	s_nop 1
	v_pk_mul_f32 v[10:11], v[2:3], v[2:3]
	v_max_f32_e32 v4, 0, v4
	v_max_f32_e32 v6, 0, v6
	v_max_f32_e32 v7, 0, v7
	v_max_f32_e32 v2, 0, v8
	v_max_f32_e32 v3, 0, v9
	v_max_f32_e32 v5, 0, v5
	v_pk_mul_f32 v[6:7], v[6:7], v[6:7]
	v_pk_mul_f32 v[8:9], v[2:3], v[2:3]
	v_pk_mul_f32 v[12:13], v[4:5], v[4:5]
	v_cvt_pk_bf16_f32 v2, v6, v7
	v_cvt_pk_bf16_f32 v3, v8, v9
	v_cvt_pk_bf16_f32 v4, v10, v11
	v_cvt_pk_bf16_f32 v5, v12, v13
	s_andn2_b64 vcc, exec, s[4:5]
	s_mov_b64 s[4:5], -1
	global_store_dwordx4 v[14:15], v[2:5], off offset:256
	s_cbranch_vccnz .LBB0_1615
	s_branch .LBB0_1614
